# P0 prologue: L2 warm-up loads for the adaLN and pos@w1 weight rows (one line per lane) before their dependent k-loops, adaLN loop issues all 8 loads before waiting
# speedup vs baseline: 1.0075x; 1.0056x over previous
; __device__ __forceinline__ void phase0(const Params& p, LAS unsigned char* lds, int tid, int lane, int wave) {
;     ...
;             const int colj = tid & 31, kg = tid >> 5, j0 = it * 32;
;             float acc[16];
; #pragma unroll
;             for (int b = 0; b < 16; ++b) acc[b] = 0.f;
;             for (int k8 = kg * 64; k8 < kg * 64 + 64; k8 += 8) {
;                 float w[8];
; #pragma unroll
;                 for (int u = 0; u < 8; ++u) w[u] = ada_w[(size_t)(k8 + u) * 6144 + j0 + colj];
; #pragma unroll
;                 for (int u = 0; u < 8; ++u)
; #pragma unroll
;                     for (int b = 0; b < 16; ++b) acc[b] += sc[b * 1024 + k8 + u] * w[u];
;             }
.LBB0_78:
	s_or_b64 exec, exec, s[12:13]
	s_ashr_i32 s37, s36, 31
	v_mov_b32_e32 v30, 0
	v_lshl_add_u64 v[28:29], s[36:37], 2, v[26:27]
	s_mov_b64 s[12:13], 0
	v_mov_b32_e32 v17, v84
	v_mov_b32_e32 v85, v83
	v_mov_b32_e32 v31, v30
	v_mov_b32_e32 v40, v30
	v_mov_b32_e32 v41, v30
	v_mov_b32_e32 v32, v30
	v_mov_b32_e32 v33, v30
	v_mov_b32_e32 v34, v30
	v_mov_b32_e32 v35, v30
	v_mov_b32_e32 v38, v30
	v_mov_b32_e32 v39, v30
	v_mov_b32_e32 v36, v30
	v_mov_b32_e32 v37, v30
	v_mov_b32_e32 v44, v30
	v_mov_b32_e32 v45, v30
	v_mov_b32_e32 v42, v30
	v_mov_b32_e32 v43, v30
	v_mbcnt_lo_u32_b32 v6, -1, 0
	v_mbcnt_hi_u32_b32 v6, -1, v6
	v_and_b32_e32 v6, 31, v6
	v_and_b32_e32 v8, 7, v6
	v_and_b32_e32 v9, 24, v6
	v_lshl_add_u32 v8, v9, 1, v8
	v_mul_u32_u24_e32 v8, 0x6000, v8
	v_lshlrev_b32_e32 v6, 2, v6
	v_sub_u32_e32 v6, v8, v6
	v_add_u32_e32 v6, 0xfffd6000, v6
	v_ashrrev_i32_e32 v7, 31, v6
	v_lshl_add_u64 v[6:7], v[6:7], 0, v[28:29]
	v_lshl_add_u64 v[8:9], v[6:7], 0, s[38:39]
	global_load_dword v66, v[6:7], off
	global_load_dword v66, v[8:9], off
	s_waitcnt lgkmcnt(0)
	s_barrier
.LBB0_79:
	v_add_co_u32_e32 v6, vcc, s59, v28
	v_add_u32_e32 v85, 8, v85
	s_nop 0
	v_addc_co_u32_e32 v7, vcc, -1, v29, vcc
	global_load_dword v66, v[6:7], off
	v_add_co_u32_e32 v6, vcc, s60, v28
	s_nop 1
	v_addc_co_u32_e32 v7, vcc, -1, v29, vcc
	global_load_dword v67, v[6:7], off
	v_add_co_u32_e32 v6, vcc, s61, v28
	s_nop 1
	v_addc_co_u32_e32 v7, vcc, -1, v29, vcc
	global_load_dword v68, v[6:7], off
	v_add_co_u32_e32 v6, vcc, s62, v28
	s_nop 1
	v_addc_co_u32_e32 v7, vcc, -1, v29, vcc
	global_load_dword v69, v[6:7], off
	v_add_co_u32_e32 v6, vcc, s63, v28
	s_nop 1
	v_addc_co_u32_e32 v7, vcc, -1, v29, vcc
	global_load_dword v64, v[6:7], off
	v_add_co_u32_e32 v6, vcc, s64, v28
	s_nop 1
	v_addc_co_u32_e32 v7, vcc, -1, v29, vcc
	global_load_dword v65, v[6:7], off
	v_add_co_u32_e32 v6, vcc, s65, v28
	s_nop 1
	v_addc_co_u32_e32 v7, vcc, -1, v29, vcc
	global_load_dword v60, v[6:7], off
	global_load_dword v62, v[28:29], off
	ds_read_b128 v[6:9], v17 offset:57344
	ds_read_b128 v[10:13], v17 offset:61440
	v_cmp_ge_i32_e32 vcc, v85, v77
	v_lshl_add_u64 v[28:29], v[28:29], 0, s[38:39]
	s_or_b64 s[12:13], vcc, s[12:13]
	s_waitcnt vmcnt(2)
	v_mov_b32_e32 v72, v67
	v_mov_b32_e32 v74, v69
	v_mov_b32_e32 v70, v65
	s_waitcnt lgkmcnt(1)
	v_mul_f32_e32 v56, v66, v6
	v_mul_f32_e32 v48, v67, v7
	s_waitcnt lgkmcnt(0)
	v_pk_mul_f32 v[58:59], v[66:67], v[10:11]
	v_mul_f32_e32 v52, v68, v8
	v_mul_f32_e32 v46, v69, v9
	v_pk_mul_f32 v[54:55], v[68:69], v[12:13]
	ds_read_b128 v[6:9], v17 offset:57360
	ds_read_b128 v[10:13], v17 offset:61456
	ds_read_b128 v[86:89], v17
	ds_read_b128 v[90:93], v17 offset:16
	ds_read_b128 v[94:97], v17 offset:4096
	v_mov_b32_e32 v57, v58
	v_pk_add_f32 v[30:31], v[30:31], v[56:57]
	s_waitcnt lgkmcnt(2)
	v_mov_b32_e32 v98, v86
	v_mov_b32_e32 v86, v88
	s_waitcnt lgkmcnt(0)
	v_mov_b32_e32 v99, v94
	v_pk_fma_f32 v[40:41], v[66:67], v[98:99], v[40:41] op_sel_hi:[0,1,1]
	v_mov_b32_e32 v94, v87
	v_pk_fma_f32 v[40:41], v[72:73], v[94:95], v[40:41] op_sel_hi:[0,1,1]
	v_mov_b32_e32 v87, v96
	v_pk_fma_f32 v[40:41], v[68:69], v[86:87], v[40:41] op_sel_hi:[0,1,1]
	v_mov_b32_e32 v96, v89
	ds_read_b128 v[86:89], v17 offset:4112
	v_pk_fma_f32 v[40:41], v[74:75], v[96:97], v[40:41] op_sel_hi:[0,1,1]
	v_mov_b32_e32 v94, v90
	v_mov_b32_e32 v49, v59
	v_pk_add_f32 v[30:31], v[30:31], v[48:49]
	s_waitcnt lgkmcnt(0)
	v_mov_b32_e32 v95, v86
	v_pk_fma_f32 v[40:41], v[64:65], v[94:95], v[40:41] op_sel_hi:[0,1,1]
	v_mov_b32_e32 v86, v91
	v_pk_fma_f32 v[40:41], v[70:71], v[86:87], v[40:41] op_sel_hi:[0,1,1]
	v_mov_b32_e32 v86, v92
	v_mov_b32_e32 v87, v88
	v_mov_b32_e32 v88, v93
	v_mov_b32_e32 v53, v54
	v_mul_f32_e32 v50, v64, v6
	v_mul_f32_e32 v6, v65, v7
	v_pk_mul_f32 v[10:11], v[64:65], v[10:11]
	v_pk_add_f32 v[30:31], v[30:31], v[52:53]
	v_mov_b32_e32 v47, v55
	v_pk_add_f32 v[30:31], v[30:31], v[46:47]
	v_mov_b32_e32 v51, v10
	v_pk_add_f32 v[30:31], v[30:31], v[50:51]
	v_mov_b32_e32 v7, v11
	v_pk_add_f32 v[6:7], v[30:31], v[6:7]
	s_waitcnt vmcnt(1)
	v_pk_fma_f32 v[40:41], v[60:61], v[86:87], v[40:41] op_sel_hi:[0,1,1]
	s_waitcnt vmcnt(0)
	v_pk_fma_f32 v[40:41], v[62:63], v[88:89], v[40:41] op_sel_hi:[0,1,1]
	ds_read_b128 v[86:89], v17 offset:8192
	ds_read_b128 v[90:93], v17 offset:12288
	v_mul_f32_e32 v8, v60, v8
	s_waitcnt lgkmcnt(1)
	v_mov_b32_e32 v94, v86
	s_waitcnt lgkmcnt(0)
	v_mov_b32_e32 v95, v90
	v_pk_fma_f32 v[32:33], v[66:67], v[94:95], v[32:33] op_sel_hi:[0,1,1]
	v_mov_b32_e32 v90, v87
	v_pk_fma_f32 v[32:33], v[72:73], v[90:91], v[32:33] op_sel_hi:[0,1,1]
	v_mov_b32_e32 v86, v88
	v_mov_b32_e32 v87, v92
	v_pk_fma_f32 v[32:33], v[68:69], v[86:87], v[32:33] op_sel_hi:[0,1,1]
	v_mov_b32_e32 v92, v89
	v_pk_fma_f32 v[32:33], v[74:75], v[92:93], v[32:33] op_sel_hi:[0,1,1]
	ds_read_b128 v[86:89], v17 offset:8208
	ds_read_b128 v[90:93], v17 offset:12304
	s_waitcnt lgkmcnt(1)
	v_mov_b32_e32 v94, v86
	s_waitcnt lgkmcnt(0)
	v_mov_b32_e32 v95, v90
	v_pk_fma_f32 v[32:33], v[64:65], v[94:95], v[32:33] op_sel_hi:[0,1,1]
	v_mov_b32_e32 v90, v87
	v_pk_fma_f32 v[32:33], v[70:71], v[90:91], v[32:33] op_sel_hi:[0,1,1]
	v_mov_b32_e32 v86, v88
	v_mov_b32_e32 v87, v92
	v_pk_fma_f32 v[32:33], v[60:61], v[86:87], v[32:33] op_sel_hi:[0,1,1]
	v_mov_b32_e32 v92, v89
	v_pk_fma_f32 v[32:33], v[62:63], v[92:93], v[32:33] op_sel_hi:[0,1,1]
	ds_read_b128 v[86:89], v17 offset:16384
	ds_read_b128 v[90:93], v17 offset:20480
	s_waitcnt lgkmcnt(1)
	v_mov_b32_e32 v94, v86
	s_waitcnt lgkmcnt(0)
; __device__ __forceinline__ void phase0(const Params& p, LAS unsigned char* lds, int tid, int lane, int wave) {
;     ...
;             for (int k8 = kg * 64; k8 < kg * 64 + 64; k8 += 8) {
;                 float w[8];
; #pragma unroll
;                 for (int u = 0; u < 8; ++u) w[u] = ada_w[(size_t)(k8 + u) * 6144 + j0 + colj];
; #pragma unroll
;                 for (int u = 0; u < 8; ++u)
; #pragma unroll
;                     for (int b = 0; b < 16; ++b) acc[b] += sc[b * 1024 + k8 + u] * w[u];
;             }
	v_mov_b32_e32 v95, v90
	v_pk_fma_f32 v[34:35], v[66:67], v[94:95], v[34:35] op_sel_hi:[0,1,1]
	v_mov_b32_e32 v90, v87
	v_pk_fma_f32 v[34:35], v[72:73], v[90:91], v[34:35] op_sel_hi:[0,1,1]
	v_mov_b32_e32 v86, v88
	v_mov_b32_e32 v87, v92
	v_pk_fma_f32 v[34:35], v[68:69], v[86:87], v[34:35] op_sel_hi:[0,1,1]
	v_mov_b32_e32 v92, v89
	v_pk_fma_f32 v[34:35], v[74:75], v[92:93], v[34:35] op_sel_hi:[0,1,1]
	ds_read_b128 v[86:89], v17 offset:16400
	ds_read_b128 v[90:93], v17 offset:20496
	s_waitcnt lgkmcnt(1)
	v_mov_b32_e32 v94, v86
	s_waitcnt lgkmcnt(0)
	v_mov_b32_e32 v95, v90
	v_pk_fma_f32 v[34:35], v[64:65], v[94:95], v[34:35] op_sel_hi:[0,1,1]
	v_mov_b32_e32 v90, v87
	v_pk_fma_f32 v[34:35], v[70:71], v[90:91], v[34:35] op_sel_hi:[0,1,1]
	v_mov_b32_e32 v86, v88
	v_mov_b32_e32 v87, v92
	v_pk_fma_f32 v[34:35], v[60:61], v[86:87], v[34:35] op_sel_hi:[0,1,1]
	v_mov_b32_e32 v92, v89
	v_pk_fma_f32 v[34:35], v[62:63], v[92:93], v[34:35] op_sel_hi:[0,1,1]
	ds_read_b128 v[86:89], v17 offset:24576
	ds_read_b128 v[90:93], v17 offset:28672
	s_waitcnt lgkmcnt(1)
	v_mov_b32_e32 v94, v86
	s_waitcnt lgkmcnt(0)
	v_mov_b32_e32 v95, v90
	v_pk_fma_f32 v[38:39], v[66:67], v[94:95], v[38:39] op_sel_hi:[0,1,1]
	v_mov_b32_e32 v90, v87
	v_pk_fma_f32 v[38:39], v[72:73], v[90:91], v[38:39] op_sel_hi:[0,1,1]
	v_mov_b32_e32 v86, v88
	v_mov_b32_e32 v87, v92
	v_pk_fma_f32 v[38:39], v[68:69], v[86:87], v[38:39] op_sel_hi:[0,1,1]
	v_mov_b32_e32 v92, v89
	v_pk_fma_f32 v[38:39], v[74:75], v[92:93], v[38:39] op_sel_hi:[0,1,1]
	ds_read_b128 v[86:89], v17 offset:24592
	ds_read_b128 v[90:93], v17 offset:28688
	s_waitcnt lgkmcnt(1)
	v_mov_b32_e32 v94, v86
	s_waitcnt lgkmcnt(0)
	v_mov_b32_e32 v95, v90
	v_pk_fma_f32 v[38:39], v[64:65], v[94:95], v[38:39] op_sel_hi:[0,1,1]
	v_mov_b32_e32 v90, v87
	v_pk_fma_f32 v[38:39], v[70:71], v[90:91], v[38:39] op_sel_hi:[0,1,1]
	v_mov_b32_e32 v86, v88
	v_mov_b32_e32 v87, v92
	v_pk_fma_f32 v[38:39], v[60:61], v[86:87], v[38:39] op_sel_hi:[0,1,1]
	v_mov_b32_e32 v92, v89
	v_pk_fma_f32 v[38:39], v[62:63], v[92:93], v[38:39] op_sel_hi:[0,1,1]
	ds_read_b128 v[86:89], v17 offset:32768
	ds_read_b128 v[90:93], v17 offset:36864
	s_waitcnt lgkmcnt(1)
	v_mov_b32_e32 v94, v86
	s_waitcnt lgkmcnt(0)
	v_mov_b32_e32 v95, v90
	v_pk_fma_f32 v[36:37], v[66:67], v[94:95], v[36:37] op_sel_hi:[0,1,1]
	v_mov_b32_e32 v90, v87
	v_pk_fma_f32 v[36:37], v[72:73], v[90:91], v[36:37] op_sel_hi:[0,1,1]
	v_mov_b32_e32 v86, v88
	v_mov_b32_e32 v87, v92
	v_pk_fma_f32 v[36:37], v[68:69], v[86:87], v[36:37] op_sel_hi:[0,1,1]
	v_mov_b32_e32 v92, v89
	v_pk_fma_f32 v[36:37], v[74:75], v[92:93], v[36:37] op_sel_hi:[0,1,1]
	ds_read_b128 v[86:89], v17 offset:32784
	ds_read_b128 v[90:93], v17 offset:36880
	s_waitcnt lgkmcnt(1)
	v_mov_b32_e32 v94, v86
	s_waitcnt lgkmcnt(0)
	v_mov_b32_e32 v95, v90
	v_pk_fma_f32 v[36:37], v[64:65], v[94:95], v[36:37] op_sel_hi:[0,1,1]
	v_mov_b32_e32 v90, v87
	v_pk_fma_f32 v[36:37], v[70:71], v[90:91], v[36:37] op_sel_hi:[0,1,1]
	v_mov_b32_e32 v86, v88
	v_mov_b32_e32 v87, v92
	v_pk_fma_f32 v[36:37], v[60:61], v[86:87], v[36:37] op_sel_hi:[0,1,1]
	v_mov_b32_e32 v92, v89
	v_pk_fma_f32 v[36:37], v[62:63], v[92:93], v[36:37] op_sel_hi:[0,1,1]
	ds_read_b128 v[86:89], v17 offset:40960
	ds_read_b128 v[90:93], v17 offset:45056
	s_waitcnt lgkmcnt(1)
	v_mov_b32_e32 v94, v86
	s_waitcnt lgkmcnt(0)
	v_mov_b32_e32 v95, v90
	v_pk_fma_f32 v[44:45], v[66:67], v[94:95], v[44:45] op_sel_hi:[0,1,1]
	v_mov_b32_e32 v90, v87
	v_pk_fma_f32 v[44:45], v[72:73], v[90:91], v[44:45] op_sel_hi:[0,1,1]
	v_mov_b32_e32 v86, v88
	v_mov_b32_e32 v87, v92
	v_pk_fma_f32 v[44:45], v[68:69], v[86:87], v[44:45] op_sel_hi:[0,1,1]
	v_mov_b32_e32 v92, v89
	v_pk_fma_f32 v[44:45], v[74:75], v[92:93], v[44:45] op_sel_hi:[0,1,1]
	ds_read_b128 v[86:89], v17 offset:40976
	ds_read_b128 v[90:93], v17 offset:45072
	s_waitcnt lgkmcnt(1)
	v_mov_b32_e32 v94, v86
	s_waitcnt lgkmcnt(0)
	v_mov_b32_e32 v95, v90
	v_pk_fma_f32 v[44:45], v[64:65], v[94:95], v[44:45] op_sel_hi:[0,1,1]
	v_mov_b32_e32 v90, v87
	v_pk_fma_f32 v[44:45], v[70:71], v[90:91], v[44:45] op_sel_hi:[0,1,1]
	v_mov_b32_e32 v86, v88
	v_mov_b32_e32 v87, v92
	v_pk_fma_f32 v[44:45], v[60:61], v[86:87], v[44:45] op_sel_hi:[0,1,1]
	v_mov_b32_e32 v92, v89
	v_pk_fma_f32 v[44:45], v[62:63], v[92:93], v[44:45] op_sel_hi:[0,1,1]
	ds_read_b128 v[86:89], v17 offset:49152
	ds_read_b128 v[90:93], v17 offset:53248
	s_waitcnt lgkmcnt(1)
	v_mov_b32_e32 v94, v86
	s_waitcnt lgkmcnt(0)
	v_mov_b32_e32 v95, v90
	v_pk_fma_f32 v[42:43], v[66:67], v[94:95], v[42:43] op_sel_hi:[0,1,1]
	v_mov_b32_e32 v90, v87
	v_pk_fma_f32 v[42:43], v[72:73], v[90:91], v[42:43] op_sel_hi:[0,1,1]
	v_mov_b32_e32 v66, v88
	v_mov_b32_e32 v67, v92
	v_pk_fma_f32 v[42:43], v[68:69], v[66:67], v[42:43] op_sel_hi:[0,1,1]
	v_mov_b32_e32 v92, v89
	ds_read_b128 v[66:69], v17 offset:49168
	ds_read_b128 v[86:89], v17 offset:53264
	v_pk_fma_f32 v[42:43], v[74:75], v[92:93], v[42:43] op_sel_hi:[0,1,1]
	v_add_u32_e32 v17, 32, v17
	s_waitcnt lgkmcnt(1)
	v_mov_b32_e32 v90, v66
	s_waitcnt lgkmcnt(0)
	v_mov_b32_e32 v91, v86
	v_pk_fma_f32 v[42:43], v[64:65], v[90:91], v[42:43] op_sel_hi:[0,1,1]
	v_mov_b32_e32 v86, v67
	v_pk_fma_f32 v[42:43], v[70:71], v[86:87], v[42:43] op_sel_hi:[0,1,1]
	v_mov_b32_e32 v64, v68
	v_mov_b32_e32 v65, v88
	v_pk_fma_f32 v[42:43], v[60:61], v[64:65], v[42:43] op_sel_hi:[0,1,1]
	v_mov_b32_e32 v61, v62
	v_pk_mul_f32 v[12:13], v[60:61], v[12:13]
	v_mul_f32_e32 v64, v62, v9
	v_mov_b32_e32 v9, v12
	v_mov_b32_e32 v88, v69
	v_pk_add_f32 v[6:7], v[6:7], v[8:9]
	v_mov_b32_e32 v65, v13
	v_pk_fma_f32 v[42:43], v[62:63], v[88:89], v[42:43] op_sel_hi:[0,1,1]
	v_pk_add_f32 v[30:31], v[6:7], v[64:65]
	s_andn2_b64 exec, exec, s[12:13]
	s_cbranch_execnz .LBB0_79
; __device__ __forceinline__ void phase0(const Params& p, LAS unsigned char* lds, int tid, int lane, int wave) {
;     ...
;             for (int b = 0; b < 16; ++b) red[(kg * 16 + b) * 32 + colj] = acc[b];
;             __syncthreads();
;             { const int b = tid >> 5, cj = tid & 31; float s = ada_b[j0 + cj];
; #pragma unroll
;               for (int k2 = 0; k2 < 16; ++k2) s += red[(k2 * 16 + b) * 32 + cj];
;               mod[b * 6144 + j0 + cj] = s; }
;             __syncthreads();
	s_or_b64 exec, exec, s[12:13]
	s_lshl_b32 s12, s30, 5
	v_add_u32_e32 v6, 0x400, v71
	ds_write2_b32 v71, v40, v41 offset1:32
	ds_write2_b32 v71, v32, v33 offset0:64 offset1:96
	ds_write2_b32 v71, v34, v35 offset0:128 offset1:160
	ds_write2_b32 v71, v38, v39 offset0:192 offset1:224
	ds_write2_b32 v6, v36, v37 offset1:32
	ds_write2_b32 v6, v44, v45 offset0:64 offset1:96
	ds_write2_b32 v6, v42, v43 offset0:128 offset1:160
	ds_write2_b32 v6, v30, v31 offset0:192 offset1:224
	v_or_b32_e32 v6, s12, v1
	v_ashrrev_i32_e32 v7, 31, v6
	v_lshl_add_u64 v[6:7], v[6:7], 2, s[80:81]
	s_waitcnt lgkmcnt(0)
	s_barrier
	global_load_dword v17, v[6:7], off
	ds_read2st64_b32 v[6:7], v73 offset1:8
	ds_read2st64_b32 v[8:9], v73 offset0:16 offset1:24
	ds_read2st64_b32 v[10:11], v73 offset0:32 offset1:40
	ds_read2st64_b32 v[12:13], v73 offset0:48 offset1:56
	ds_read2st64_b32 v[28:29], v73 offset0:64 offset1:72
	ds_read2st64_b32 v[30:31], v73 offset0:80 offset1:88
	ds_read2st64_b32 v[32:33], v73 offset0:96 offset1:104
	ds_read2st64_b32 v[34:35], v73 offset0:112 offset1:120
	v_add_u32_e32 v36, s12, v75
	v_ashrrev_i32_e32 v37, 31, v36
	v_lshl_add_u64 v[36:37], v[36:37], 2, s[2:3]
	s_waitcnt vmcnt(0) lgkmcnt(7)
	v_add_f32_e32 v6, v17, v6
	v_add_f32_e32 v6, v6, v7
	s_waitcnt lgkmcnt(6)
	v_add_f32_e32 v6, v6, v8
	v_add_f32_e32 v6, v6, v9
	s_waitcnt lgkmcnt(5)
	v_add_f32_e32 v6, v6, v10
	v_add_f32_e32 v6, v6, v11
	s_waitcnt lgkmcnt(4)
	v_add_f32_e32 v6, v6, v12
	v_add_f32_e32 v6, v6, v13
	s_waitcnt lgkmcnt(3)
	v_add_f32_e32 v6, v6, v28
	v_add_f32_e32 v6, v6, v29
	s_waitcnt lgkmcnt(2)
	v_add_f32_e32 v6, v6, v30
	v_add_f32_e32 v6, v6, v31
	s_waitcnt lgkmcnt(1)
	v_add_f32_e32 v6, v6, v32
	v_add_f32_e32 v6, v6, v33
	s_waitcnt lgkmcnt(0)
	v_add_f32_e32 v6, v6, v34
	v_add_f32_e32 v6, v6, v35
	global_store_dword v[36:37], v6, off
	s_barrier
	s_cbranch_execz .LBB0_53
	s_branch .LBB0_83

; __device__ __forceinline__ void phase0(const Params& p, LAS unsigned char* lds, int tid, int lane, int wave) {
;     ...
;         } else if (it < 194) {
;             const int kv = it - 192; const float* w1 = kv ? p.in[11] : p.in[9]; const float* pos = p.in[8];
;             const int colj = tid & 63, kg = tid >> 6; float a = 0.f;
;             for (int k16 = kg * 256; k16 < kg * 256 + 256; k16 += 16) {
;                 float w[16], pv_[16];
; #pragma unroll
;                 for (int u = 0; u < 16; ++u) { w[u] = w1[(k16 + u) * 64 + colj]; pv_[u] = pos[k16 + u]; }
; #pragma unroll
;                 for (int u = 0; u < 16; ++u) a += pv_[u] * w[u];
;             }
.LBB0_85:
	s_add_i32 s35, s30, 0xffffff40
	s_cmp_eq_u32 s35, 0
	s_cselect_b32 s41, s15, s19
	s_cselect_b32 s40, s14, s18
	v_mov_b32_e32 v11, 0
	s_mov_b64 s[42:43], 0
	v_mov_b64_e32 v[6:7], v[22:23]
	v_mov_b32_e32 v8, v81
	v_mov_b32_e32 v10, v80
	v_mbcnt_lo_u32_b32 v12, -1, 0
	v_mbcnt_hi_u32_b32 v12, -1, v12
	v_mul_u32_u24_e32 v12, 31, v12
	v_add_u32_e32 v12, v12, v81
	v_add_u32_e32 v12, 0xfffffc40, v12
	v_mov_b32_e32 v28, v12
	v_ashrrev_i32_e32 v29, 31, v28
	v_lshl_add_u64 v[28:29], v[28:29], 2, s[40:41]
	v_add_u32_e32 v30, 0x800, v12
	v_ashrrev_i32_e32 v31, 31, v30
	v_lshl_add_u64 v[30:31], v[30:31], 2, s[40:41]
	v_add_u32_e32 v32, 0x1000, v12
	v_ashrrev_i32_e32 v33, 31, v32
	v_lshl_add_u64 v[32:33], v[32:33], 2, s[40:41]
	v_add_u32_e32 v34, 0x1800, v12
	v_ashrrev_i32_e32 v35, 31, v34
	v_lshl_add_u64 v[34:35], v[34:35], 2, s[40:41]
	v_add_u32_e32 v36, 0x2000, v12
	v_ashrrev_i32_e32 v37, 31, v36
	v_lshl_add_u64 v[36:37], v[36:37], 2, s[40:41]
	v_add_u32_e32 v38, 0x2800, v12
	v_ashrrev_i32_e32 v39, 31, v38
	v_lshl_add_u64 v[38:39], v[38:39], 2, s[40:41]
	v_add_u32_e32 v40, 0x3000, v12
	v_ashrrev_i32_e32 v41, 31, v40
	v_lshl_add_u64 v[40:41], v[40:41], 2, s[40:41]
	v_add_u32_e32 v42, 0x3800, v12
	v_ashrrev_i32_e32 v43, 31, v42
	v_lshl_add_u64 v[42:43], v[42:43], 2, s[40:41]
	global_load_dword v17, v[28:29], off
	global_load_dword v17, v[30:31], off
	global_load_dword v17, v[32:33], off
	global_load_dword v17, v[34:35], off
	global_load_dword v17, v[36:37], off
	global_load_dword v17, v[38:39], off
	global_load_dword v17, v[40:41], off
	global_load_dword v17, v[42:43], off
